# s_setprio toggles removed from the FFN gate/up GEMM K loop (16 scalar instructions per K step)
# baseline (speedup 1.0000x reference)
; #define PG8_STAGE(bufoff, gbase, voff) do { _Pragma("unroll") for (int _i = 0; _i < 2; ++_i) \
;         __builtin_amdgcn_global_load_lds((const unsigned*)((const char*)(gbase) + (voff)[_i]), (PG8_LAS unsigned*)(lds + (bufoff) + ldsw + _i * 8192), 16, 0, 0); } while (0)
; #define PG8_LDA(dst, b, h) do { _Pragma("unroll") for (int m = 0; m < 4; ++m) _Pragma("unroll") for (int k = 0; k < 2; ++k) dst[m][k] = *(const PG8_LAS bf16x8*)(lds + PG8_SA(b, h) + aoff + m * 2048 + k * 1024); } while (0)
; #define PG8_LDB(dst, b, h) do { _Pragma("unroll") for (int n = 0; n < 2; ++n) _Pragma("unroll") for (int k = 0; k < 2; ++k) dst[n][k] = *(const PG8_LAS bf16x8*)(lds + PG8_SB(b, h) + boff + n * 2048 + k * 1024); } while (0)
; #define PG8_MMA(ai, bj, At, Bt) do { __builtin_amdgcn_s_setprio(1); _Pragma("unroll") for (int m = 0; m < 4; ++m) _Pragma("unroll") for (int n = 0; n < 2; ++n) _Pragma("unroll") for (int k = 0; k < 2; ++k) \
;         acc[ai][bj][m][n] = __builtin_amdgcn_mfma_f32_16x16x32_bf16(Bt[n][k], At[m][k], acc[ai][bj][m][n], 0, 0, 0); __builtin_amdgcn_s_setprio(0); } while (0)
; #define PG8_WAIT_V(n) asm volatile("s_waitcnt vmcnt(" #n ")" ::: "memory")
; #define PG8_WAIT_L(n) asm volatile("s_waitcnt lgkmcnt(" #n ")" ::: "memory")
; #define PG8_BAR __builtin_amdgcn_s_barrier()
; #define PG8_SCHED __builtin_amdgcn_sched_barrier(0)
; template <class Epi, class Sched, bool ALIGN_EPI = false, bool SP2 = false>
; __device__ __forceinline__ void gemm_phase(PG8_LAS unsigned char* lds, const Gemm g, const Sched& S, const Epi& E) {
;     ...
;             PG8_LDB(B0, 0, 0); PG8_LDB(B1, 0, 1); PG8_SCHED; PG8_LDA(At, 0, 0); PG8_STAGE(PG8_SA(1, 1), a1 + hstep, voffA);
;             PG8_WAIT_V(8); PG8_WAIT_L(0); PG8_BAR; PG8_MMA(0, 0, At, B0); PG8_MMA(0, 1, At, B1); PG8_BAR; PG8_SCHED;
;             PG8_LDA(At, 0, 1); PG8_STAGE(PG8_SB(0, 0), b2, voffB); PG8_STAGE(PG8_SB(0, 1), b2 + hstep, voffB); PG8_STAGE(PG8_SA(0, 0), a2, voffA);
.LBB0_1704:
	s_add_u32 s3, s48, 0xfffc0080
	s_addc_u32 s20, s49, -1
	s_add_i32 s21, 0, 0x10000
	s_cmp_eq_u32 s72, 12
	s_cselect_b32 s55, s4, s20
	s_cselect_b32 s54, s5, s3
	s_cselect_b32 s51, s39, s71
	s_cselect_b32 s50, s41, s70
	s_add_i32 s3, 0, 0x14000
	v_add_u32_e32 v154, s21, v139
	v_add_u32_e32 v170, s3, v139
	ds_read_b128 v[142:145], v154
	ds_read_b128 v[146:149], v154 offset:1024
	ds_read_b128 v[150:153], v154 offset:2048
	ds_read_b128 v[154:157], v154 offset:3072
	ds_read_b128 v[158:161], v170
	ds_read_b128 v[162:165], v170 offset:1024
	ds_read_b128 v[166:169], v170 offset:2048
	ds_read_b128 v[170:173], v170 offset:3072
	v_lshl_add_u64 v[206:207], s[48:49], 0, v[134:135]
	s_add_i32 m0, s47, 0xc000
	ds_read_b128 v[174:177], v141
	ds_read_b128 v[178:181], v141 offset:1024
	ds_read_b128 v[182:185], v141 offset:2048
	ds_read_b128 v[186:189], v141 offset:3072
	ds_read_b128 v[190:193], v141 offset:4096
	ds_read_b128 v[194:197], v141 offset:5120
	ds_read_b128 v[198:201], v141 offset:6144
	ds_read_b128 v[202:205], v141 offset:7168
	global_load_lds_dwordx4 v[206:207], off
	v_lshl_add_u64 v[206:207], s[48:49], 0, v[136:137]
	s_add_i32 m0, s47, 0xe000
	s_nop 0
	global_load_lds_dwordx4 v[206:207], off
	s_waitcnt vmcnt(8)
	s_waitcnt lgkmcnt(0)
	s_barrier
	s_waitcnt lgkmcnt(0)
	v_mfma_f32_16x16x32_bf16 v[124:127], v[142:145], v[174:177], v[124:127]
	v_mfma_f32_16x16x32_bf16 v[116:119], v[150:153], v[174:177], v[116:119]
	v_mfma_f32_16x16x32_bf16 v[108:111], v[142:145], v[182:185], v[108:111]
	v_mfma_f32_16x16x32_bf16 v[100:103], v[150:153], v[182:185], v[100:103]
	v_mfma_f32_16x16x32_bf16 v[92:95], v[142:145], v[190:193], v[92:95]
	v_mfma_f32_16x16x32_bf16 v[84:87], v[150:153], v[190:193], v[84:87]
	v_mfma_f32_16x16x32_bf16 v[76:79], v[142:145], v[198:201], v[76:79]
	v_mfma_f32_16x16x32_bf16 v[68:71], v[150:153], v[198:201], v[68:71]
	v_mfma_f32_16x16x32_bf16 v[124:127], v[146:149], v[178:181], v[124:127]
	v_mfma_f32_16x16x32_bf16 v[116:119], v[154:157], v[178:181], v[116:119]
	v_mfma_f32_16x16x32_bf16 v[108:111], v[146:149], v[186:189], v[108:111]
	v_mfma_f32_16x16x32_bf16 v[100:103], v[154:157], v[186:189], v[100:103]
	v_mfma_f32_16x16x32_bf16 v[92:95], v[146:149], v[194:197], v[92:95]
	v_mfma_f32_16x16x32_bf16 v[84:87], v[154:157], v[194:197], v[84:87]
	v_mfma_f32_16x16x32_bf16 v[76:79], v[146:149], v[202:205], v[76:79]
	v_mfma_f32_16x16x32_bf16 v[68:71], v[154:157], v[202:205], v[68:71]
	v_mfma_f32_16x16x32_bf16 v[120:123], v[158:161], v[174:177], v[120:123]
	v_mfma_f32_16x16x32_bf16 v[112:115], v[166:169], v[174:177], v[112:115]
	v_mfma_f32_16x16x32_bf16 v[104:107], v[158:161], v[182:185], v[104:107]
	v_mfma_f32_16x16x32_bf16 v[96:99], v[166:169], v[182:185], v[96:99]
	v_mfma_f32_16x16x32_bf16 v[88:91], v[158:161], v[190:193], v[88:91]
	v_mfma_f32_16x16x32_bf16 v[80:83], v[166:169], v[190:193], v[80:83]
	v_mfma_f32_16x16x32_bf16 v[72:75], v[158:161], v[198:201], v[72:75]
	v_mfma_f32_16x16x32_bf16 v[64:67], v[166:169], v[198:201], v[64:67]
	v_mfma_f32_16x16x32_bf16 v[120:123], v[162:165], v[178:181], v[120:123]
	v_mfma_f32_16x16x32_bf16 v[112:115], v[170:173], v[178:181], v[112:115]
	v_mfma_f32_16x16x32_bf16 v[104:107], v[162:165], v[186:189], v[104:107]
	v_mfma_f32_16x16x32_bf16 v[96:99], v[170:173], v[186:189], v[96:99]
	v_mfma_f32_16x16x32_bf16 v[88:91], v[162:165], v[194:197], v[88:91]
	v_mfma_f32_16x16x32_bf16 v[80:83], v[170:173], v[194:197], v[80:83]
	v_mfma_f32_16x16x32_bf16 v[72:75], v[162:165], v[202:205], v[72:75]
	v_mfma_f32_16x16x32_bf16 v[64:67], v[170:173], v[202:205], v[64:67]
	s_barrier
	s_add_i32 s20, s21, s19
	v_lshl_add_u64 v[206:207], s[50:51], 0, v[232:233]
	s_mov_b32 m0, s20
	ds_read_b128 v[174:177], v141 offset:16384
	ds_read_b128 v[178:181], v141 offset:17408
	ds_read_b128 v[182:185], v141 offset:18432
	ds_read_b128 v[186:189], v141 offset:19456
	ds_read_b128 v[190:193], v141 offset:20480
	ds_read_b128 v[194:197], v141 offset:21504
	ds_read_b128 v[198:201], v141 offset:22528
	ds_read_b128 v[202:205], v141 offset:23552
	global_load_lds_dwordx4 v[206:207], off
	s_add_i32 m0, s20, 0x2000
	s_add_u32 s90, s50, 0x40000
	v_lshl_add_u64 v[208:209], s[50:51], 0, v[128:129]
	s_addc_u32 s91, s51, 0
	s_add_i32 s3, s3, s19
	global_load_lds_dwordx4 v[208:209], off
	v_lshl_add_u64 v[210:211], s[90:91], 0, v[232:233]
	s_mov_b32 m0, s3
	v_lshl_add_u64 v[212:213], s[54:55], 0, v[130:131]
	global_load_lds_dwordx4 v[210:211], off
	v_lshl_add_u64 v[210:211], s[90:91], 0, v[128:129]
	s_add_i32 m0, s3, 0x2000
	s_nop 0
	global_load_lds_dwordx4 v[210:211], off
	v_lshl_add_u64 v[210:211], s[54:55], 0, v[132:133]
	s_mov_b32 m0, s47
	s_nop 0
	global_load_lds_dwordx4 v[210:211], off
	s_mov_b32 m0, s59
	s_nop 0
	global_load_lds_dwordx4 v[212:213], off
	s_waitcnt vmcnt(8)
	s_waitcnt lgkmcnt(0)
	s_barrier
; #define PG8_STAGE(bufoff, gbase, voff) do { _Pragma("unroll") for (int _i = 0; _i < 2; ++_i) \
;         __builtin_amdgcn_global_load_lds((const unsigned*)((const char*)(gbase) + (voff)[_i]), (PG8_LAS unsigned*)(lds + (bufoff) + ldsw + _i * 8192), 16, 0, 0); } while (0)
; #define PG8_LDA(dst, b, h) do { _Pragma("unroll") for (int m = 0; m < 4; ++m) _Pragma("unroll") for (int k = 0; k < 2; ++k) dst[m][k] = *(const PG8_LAS bf16x8*)(lds + PG8_SA(b, h) + aoff + m * 2048 + k * 1024); } while (0)
; #define PG8_LDB(dst, b, h) do { _Pragma("unroll") for (int n = 0; n < 2; ++n) _Pragma("unroll") for (int k = 0; k < 2; ++k) dst[n][k] = *(const PG8_LAS bf16x8*)(lds + PG8_SB(b, h) + boff + n * 2048 + k * 1024); } while (0)
; #define PG8_MMA(ai, bj, At, Bt) do { __builtin_amdgcn_s_setprio(1); _Pragma("unroll") for (int m = 0; m < 4; ++m) _Pragma("unroll") for (int n = 0; n < 2; ++n) _Pragma("unroll") for (int k = 0; k < 2; ++k) \
;         acc[ai][bj][m][n] = __builtin_amdgcn_mfma_f32_16x16x32_bf16(Bt[n][k], At[m][k], acc[ai][bj][m][n], 0, 0, 0); __builtin_amdgcn_s_setprio(0); } while (0)
; #define PG8_WAIT_V(n) asm volatile("s_waitcnt vmcnt(" #n ")" ::: "memory")
; #define PG8_WAIT_L(n) asm volatile("s_waitcnt lgkmcnt(" #n ")" ::: "memory")
; #define PG8_BAR __builtin_amdgcn_s_barrier()
; #define PG8_SCHED __builtin_amdgcn_sched_barrier(0)
; template <class Epi, class Sched, bool ALIGN_EPI = false, bool SP2 = false>
; __device__ __forceinline__ void gemm_phase(PG8_LAS unsigned char* lds, const Gemm g, const Sched& S, const Epi& E) {
;     ...
;             PG8_WAIT_V(8); PG8_WAIT_L(0); PG8_BAR; PG8_MMA(1, 0, At, B0); PG8_MMA(1, 1, At, B1); PG8_BAR; PG8_SCHED;
;             PG8_LDB(B0, 1, 0); PG8_LDB(B1, 1, 1); PG8_SCHED; PG8_LDA(At, 1, 0); PG8_STAGE(PG8_SA(0, 1), a2 + hstep, voffA);
;             PG8_WAIT_V(8); PG8_WAIT_L(0); PG8_BAR; PG8_MMA(0, 0, At, B0); PG8_MMA(0, 1, At, B1); PG8_BAR; PG8_SCHED;
	s_waitcnt lgkmcnt(0)
	v_mfma_f32_16x16x32_bf16 v[60:63], v[142:145], v[174:177], v[60:63]
	v_mfma_f32_16x16x32_bf16 v[52:55], v[150:153], v[174:177], v[52:55]
	v_mfma_f32_16x16x32_bf16 v[44:47], v[142:145], v[182:185], v[44:47]
	v_mfma_f32_16x16x32_bf16 v[36:39], v[150:153], v[182:185], v[36:39]
	v_mfma_f32_16x16x32_bf16 v[28:31], v[142:145], v[190:193], v[28:31]
	v_mfma_f32_16x16x32_bf16 v[20:23], v[150:153], v[190:193], v[20:23]
	v_mfma_f32_16x16x32_bf16 v[12:15], v[142:145], v[198:201], v[12:15]
	v_mfma_f32_16x16x32_bf16 v[4:7], v[150:153], v[198:201], v[4:7]
	v_mfma_f32_16x16x32_bf16 v[60:63], v[146:149], v[178:181], v[60:63]
	v_mfma_f32_16x16x32_bf16 v[52:55], v[154:157], v[178:181], v[52:55]
	v_mfma_f32_16x16x32_bf16 v[44:47], v[146:149], v[186:189], v[44:47]
	v_mfma_f32_16x16x32_bf16 v[36:39], v[154:157], v[186:189], v[36:39]
	v_mfma_f32_16x16x32_bf16 v[28:31], v[146:149], v[194:197], v[28:31]
	v_mfma_f32_16x16x32_bf16 v[20:23], v[154:157], v[194:197], v[20:23]
	v_mfma_f32_16x16x32_bf16 v[12:15], v[146:149], v[202:205], v[12:15]
	v_mfma_f32_16x16x32_bf16 v[4:7], v[154:157], v[202:205], v[4:7]
	v_mfma_f32_16x16x32_bf16 v[56:59], v[158:161], v[174:177], v[56:59]
	v_mfma_f32_16x16x32_bf16 v[48:51], v[166:169], v[174:177], v[48:51]
	v_mfma_f32_16x16x32_bf16 v[40:43], v[158:161], v[182:185], v[40:43]
	v_mfma_f32_16x16x32_bf16 v[32:35], v[166:169], v[182:185], v[32:35]
	v_mfma_f32_16x16x32_bf16 v[24:27], v[158:161], v[190:193], v[24:27]
	v_mfma_f32_16x16x32_bf16 v[16:19], v[166:169], v[190:193], v[16:19]
	v_mfma_f32_16x16x32_bf16 v[8:11], v[158:161], v[198:201], v[8:11]
	v_mfma_f32_16x16x32_bf16 v[0:3], v[166:169], v[198:201], v[0:3]
	v_mfma_f32_16x16x32_bf16 v[56:59], v[162:165], v[178:181], v[56:59]
	v_mfma_f32_16x16x32_bf16 v[48:51], v[170:173], v[178:181], v[48:51]
	v_mfma_f32_16x16x32_bf16 v[40:43], v[162:165], v[186:189], v[40:43]
	v_mfma_f32_16x16x32_bf16 v[32:35], v[170:173], v[186:189], v[32:35]
	v_mfma_f32_16x16x32_bf16 v[24:27], v[162:165], v[194:197], v[24:27]
	v_mfma_f32_16x16x32_bf16 v[16:19], v[170:173], v[194:197], v[16:19]
	v_mfma_f32_16x16x32_bf16 v[8:11], v[162:165], v[202:205], v[8:11]
	v_mfma_f32_16x16x32_bf16 v[0:3], v[170:173], v[202:205], v[0:3]
	s_barrier
	s_add_i32 s3, 0, 0x18000
	s_add_i32 s20, 0, 0x1c000
	v_add_u32_e32 v154, s3, v139
	v_add_u32_e32 v170, s20, v139
	ds_read_b128 v[142:145], v154
	ds_read_b128 v[146:149], v154 offset:1024
	ds_read_b128 v[150:153], v154 offset:2048
	ds_read_b128 v[154:157], v154 offset:3072
	ds_read_b128 v[158:161], v170
	ds_read_b128 v[162:165], v170 offset:1024
	ds_read_b128 v[166:169], v170 offset:2048
	ds_read_b128 v[170:173], v170 offset:3072
	s_add_u32 s54, s54, 0x40000
	s_addc_u32 s55, s55, 0
	s_mov_b32 m0, s64
	v_lshl_add_u64 v[214:215], s[54:55], 0, v[132:133]
	ds_read_b128 v[174:177], v141 offset:32768
	ds_read_b128 v[178:181], v141 offset:33792
	ds_read_b128 v[182:185], v141 offset:34816
	ds_read_b128 v[186:189], v141 offset:35840
	ds_read_b128 v[190:193], v141 offset:36864
	ds_read_b128 v[194:197], v141 offset:37888
	ds_read_b128 v[198:201], v141 offset:38912
	ds_read_b128 v[202:205], v141 offset:39936
	global_load_lds_dwordx4 v[214:215], off
	v_lshl_add_u64 v[214:215], s[54:55], 0, v[130:131]
	s_mov_b32 m0, s65
	s_nop 0
	global_load_lds_dwordx4 v[214:215], off
	s_waitcnt vmcnt(8)
	s_waitcnt lgkmcnt(0)
	s_barrier
	s_waitcnt lgkmcnt(0)
	v_mfma_f32_16x16x32_bf16 v[124:127], v[142:145], v[174:177], v[124:127]
	v_mfma_f32_16x16x32_bf16 v[116:119], v[150:153], v[174:177], v[116:119]
	v_mfma_f32_16x16x32_bf16 v[108:111], v[142:145], v[182:185], v[108:111]
	v_mfma_f32_16x16x32_bf16 v[100:103], v[150:153], v[182:185], v[100:103]
	v_mfma_f32_16x16x32_bf16 v[92:95], v[142:145], v[190:193], v[92:95]
	v_mfma_f32_16x16x32_bf16 v[84:87], v[150:153], v[190:193], v[84:87]
	v_mfma_f32_16x16x32_bf16 v[76:79], v[142:145], v[198:201], v[76:79]
	v_mfma_f32_16x16x32_bf16 v[68:71], v[150:153], v[198:201], v[68:71]
	v_mfma_f32_16x16x32_bf16 v[124:127], v[146:149], v[178:181], v[124:127]
	v_mfma_f32_16x16x32_bf16 v[116:119], v[154:157], v[178:181], v[116:119]
	v_mfma_f32_16x16x32_bf16 v[108:111], v[146:149], v[186:189], v[108:111]
	v_mfma_f32_16x16x32_bf16 v[100:103], v[154:157], v[186:189], v[100:103]
	v_mfma_f32_16x16x32_bf16 v[92:95], v[146:149], v[194:197], v[92:95]
	v_mfma_f32_16x16x32_bf16 v[84:87], v[154:157], v[194:197], v[84:87]
	v_mfma_f32_16x16x32_bf16 v[76:79], v[146:149], v[202:205], v[76:79]
	v_mfma_f32_16x16x32_bf16 v[68:71], v[154:157], v[202:205], v[68:71]
	v_mfma_f32_16x16x32_bf16 v[120:123], v[158:161], v[174:177], v[120:123]
	v_mfma_f32_16x16x32_bf16 v[112:115], v[166:169], v[174:177], v[112:115]
	v_mfma_f32_16x16x32_bf16 v[104:107], v[158:161], v[182:185], v[104:107]
	v_mfma_f32_16x16x32_bf16 v[96:99], v[166:169], v[182:185], v[96:99]
	v_mfma_f32_16x16x32_bf16 v[88:91], v[158:161], v[190:193], v[88:91]
	v_mfma_f32_16x16x32_bf16 v[80:83], v[166:169], v[190:193], v[80:83]
	v_mfma_f32_16x16x32_bf16 v[72:75], v[158:161], v[198:201], v[72:75]
	v_mfma_f32_16x16x32_bf16 v[64:67], v[166:169], v[198:201], v[64:67]
	v_mfma_f32_16x16x32_bf16 v[120:123], v[162:165], v[178:181], v[120:123]
	v_mfma_f32_16x16x32_bf16 v[112:115], v[170:173], v[178:181], v[112:115]
	v_mfma_f32_16x16x32_bf16 v[104:107], v[162:165], v[186:189], v[104:107]
	v_mfma_f32_16x16x32_bf16 v[96:99], v[170:173], v[186:189], v[96:99]
	v_mfma_f32_16x16x32_bf16 v[88:91], v[162:165], v[194:197], v[88:91]
	v_mfma_f32_16x16x32_bf16 v[80:83], v[170:173], v[194:197], v[80:83]
	v_mfma_f32_16x16x32_bf16 v[72:75], v[162:165], v[202:205], v[72:75]
	v_mfma_f32_16x16x32_bf16 v[64:67], v[170:173], v[202:205], v[64:67]
	s_barrier
; #define PG8_STAGE(bufoff, gbase, voff) do { _Pragma("unroll") for (int _i = 0; _i < 2; ++_i) \
;         __builtin_amdgcn_global_load_lds((const unsigned*)((const char*)(gbase) + (voff)[_i]), (PG8_LAS unsigned*)(lds + (bufoff) + ldsw + _i * 8192), 16, 0, 0); } while (0)
; #define PG8_LDA(dst, b, h) do { _Pragma("unroll") for (int m = 0; m < 4; ++m) _Pragma("unroll") for (int k = 0; k < 2; ++k) dst[m][k] = *(const PG8_LAS bf16x8*)(lds + PG8_SA(b, h) + aoff + m * 2048 + k * 1024); } while (0)
; #define PG8_MMA(ai, bj, At, Bt) do { __builtin_amdgcn_s_setprio(1); _Pragma("unroll") for (int m = 0; m < 4; ++m) _Pragma("unroll") for (int n = 0; n < 2; ++n) _Pragma("unroll") for (int k = 0; k < 2; ++k) \
;         acc[ai][bj][m][n] = __builtin_amdgcn_mfma_f32_16x16x32_bf16(Bt[n][k], At[m][k], acc[ai][bj][m][n], 0, 0, 0); __builtin_amdgcn_s_setprio(0); } while (0)
; #define PG8_WAIT_V(n) asm volatile("s_waitcnt vmcnt(" #n ")" ::: "memory")
; #define PG8_WAIT_L(n) asm volatile("s_waitcnt lgkmcnt(" #n ")" ::: "memory")
; #define PG8_BAR __builtin_amdgcn_s_barrier()
; #define PG8_SCHED __builtin_amdgcn_sched_barrier(0)
; template <class Epi, class Sched, bool ALIGN_EPI = false, bool SP2 = false>
; __device__ __forceinline__ void gemm_phase(PG8_LAS unsigned char* lds, const Gemm g, const Sched& S, const Epi& E) {
;     ...
;         for (int t = 0; t < nt; t += 2) {
;     ...
;             PG8_LDA(At, 1, 1); PG8_STAGE(PG8_SB(1, 0), b3, voffB); PG8_STAGE(PG8_SB(1, 1), b3 + hstep, voffB); PG8_STAGE(PG8_SA(1, 0), a3, voffA);
;             PG8_WAIT_V(8); PG8_WAIT_L(0); PG8_BAR; PG8_MMA(1, 0, At, B0); PG8_MMA(1, 1, At, B1); PG8_BAR; PG8_SCHED;
	s_add_i32 s3, s3, s19
	v_lshl_add_u64 v[206:207], v[206:207], 0, s[76:77]
	s_mov_b32 m0, s3
	ds_read_b128 v[174:177], v141 offset:49152
	ds_read_b128 v[178:181], v141 offset:50176
	ds_read_b128 v[182:185], v141 offset:51200
	ds_read_b128 v[186:189], v141 offset:52224
	ds_read_b128 v[190:193], v141 offset:53248
	ds_read_b128 v[194:197], v141 offset:54272
	ds_read_b128 v[198:201], v141 offset:55296
	ds_read_b128 v[202:205], v141 offset:56320
	global_load_lds_dwordx4 v[206:207], off
	s_add_i32 m0, s3, 0x2000
	s_add_u32 s50, s50, 0x40080
	v_lshl_add_u64 v[206:207], v[208:209], 0, s[76:77]
	s_addc_u32 s51, s51, 0
	s_add_i32 s3, s20, s19
	global_load_lds_dwordx4 v[206:207], off
	v_lshl_add_u64 v[206:207], s[50:51], 0, v[232:233]
	s_mov_b32 m0, s3
	s_nop 0
	global_load_lds_dwordx4 v[206:207], off
	v_lshl_add_u64 v[206:207], s[50:51], 0, v[128:129]
	s_add_i32 m0, s3, 0x2000
	s_nop 0
	global_load_lds_dwordx4 v[206:207], off
	v_lshl_add_u64 v[206:207], v[210:211], 0, s[76:77]
	s_mov_b32 m0, s66
	s_nop 0
	global_load_lds_dwordx4 v[206:207], off
	v_lshl_add_u64 v[206:207], v[212:213], 0, s[76:77]
	s_mov_b32 m0, s67
	s_nop 0
	global_load_lds_dwordx4 v[206:207], off
	s_waitcnt vmcnt(8)
	s_waitcnt lgkmcnt(0)
	s_barrier
	s_waitcnt lgkmcnt(0)
	v_mfma_f32_16x16x32_bf16 v[60:63], v[142:145], v[174:177], v[60:63]
	v_mfma_f32_16x16x32_bf16 v[52:55], v[150:153], v[174:177], v[52:55]
	v_mfma_f32_16x16x32_bf16 v[44:47], v[142:145], v[182:185], v[44:47]
	v_mfma_f32_16x16x32_bf16 v[36:39], v[150:153], v[182:185], v[36:39]
	v_mfma_f32_16x16x32_bf16 v[28:31], v[142:145], v[190:193], v[28:31]
	v_mfma_f32_16x16x32_bf16 v[20:23], v[150:153], v[190:193], v[20:23]
	v_mfma_f32_16x16x32_bf16 v[12:15], v[142:145], v[198:201], v[12:15]
	v_mfma_f32_16x16x32_bf16 v[4:7], v[150:153], v[198:201], v[4:7]
	v_mfma_f32_16x16x32_bf16 v[60:63], v[146:149], v[178:181], v[60:63]
	v_mfma_f32_16x16x32_bf16 v[52:55], v[154:157], v[178:181], v[52:55]
	v_mfma_f32_16x16x32_bf16 v[44:47], v[146:149], v[186:189], v[44:47]
	v_mfma_f32_16x16x32_bf16 v[36:39], v[154:157], v[186:189], v[36:39]
	v_mfma_f32_16x16x32_bf16 v[28:31], v[146:149], v[194:197], v[28:31]
	v_mfma_f32_16x16x32_bf16 v[20:23], v[154:157], v[194:197], v[20:23]
	v_mfma_f32_16x16x32_bf16 v[12:15], v[146:149], v[202:205], v[12:15]
	v_mfma_f32_16x16x32_bf16 v[4:7], v[154:157], v[202:205], v[4:7]
	v_mfma_f32_16x16x32_bf16 v[56:59], v[158:161], v[174:177], v[56:59]
	v_mfma_f32_16x16x32_bf16 v[48:51], v[166:169], v[174:177], v[48:51]
	v_mfma_f32_16x16x32_bf16 v[40:43], v[158:161], v[182:185], v[40:43]
	v_mfma_f32_16x16x32_bf16 v[32:35], v[166:169], v[182:185], v[32:35]
	v_mfma_f32_16x16x32_bf16 v[24:27], v[158:161], v[190:193], v[24:27]
	v_mfma_f32_16x16x32_bf16 v[16:19], v[166:169], v[190:193], v[16:19]
	v_mfma_f32_16x16x32_bf16 v[8:11], v[158:161], v[198:201], v[8:11]
	v_mfma_f32_16x16x32_bf16 v[0:3], v[166:169], v[198:201], v[0:3]
	v_mfma_f32_16x16x32_bf16 v[56:59], v[162:165], v[178:181], v[56:59]
	v_mfma_f32_16x16x32_bf16 v[48:51], v[170:173], v[178:181], v[48:51]
	v_mfma_f32_16x16x32_bf16 v[40:43], v[162:165], v[186:189], v[40:43]
	v_mfma_f32_16x16x32_bf16 v[32:35], v[170:173], v[186:189], v[32:35]
	v_mfma_f32_16x16x32_bf16 v[24:27], v[162:165], v[194:197], v[24:27]
	v_mfma_f32_16x16x32_bf16 v[16:19], v[170:173], v[194:197], v[16:19]
	v_mfma_f32_16x16x32_bf16 v[8:11], v[162:165], v[202:205], v[8:11]
	v_mfma_f32_16x16x32_bf16 v[0:3], v[170:173], v[202:205], v[0:3]
	s_barrier
	s_add_i32 s72, s72, 2
	s_add_u32 s48, s48, 0x100
	s_addc_u32 s49, s49, 0
	s_add_u32 s70, s70, 0x100
	s_addc_u32 s71, s71, 0
	s_cmp_gt_u32 s72, 13
	s_cbranch_scc0 .LBB0_1704
	s_and_b64 vcc, exec, s[28:29]
	s_cbranch_vccz .LBB0_1707
	s_barrier
